# GEMM K-loop: per-group s_setprio flips replaced by one static s_setprio 1 for waves 4-7 (the half one barrier behind)
# speedup vs baseline: 1.0037x; 1.0037x over previous
; #define PG8_STAGE(bufoff, gbase) do { _Pragma("unroll") for (int _i = 0; _i < 2; ++_i) \
;         __builtin_amdgcn_global_load_lds((const unsigned*)((const char*)(gbase) + voff[_i]), (LAS unsigned*)(lds + (bufoff) + ldsw + _i * 8192), 16, 0, 0); } while (0)
; #define PG8_LDA(dst, b, h) do { _Pragma("unroll") for (int m = 0; m < 4; ++m) _Pragma("unroll") for (int k = 0; k < 2; ++k) dst[m][k] = *(const LAS bf16x8*)(lds + PG8_SA(b, h) + aoff + m * 2048 + k * 1024); } while (0)
; #define PG8_LDB(dst, b, h) do { _Pragma("unroll") for (int n = 0; n < 2; ++n) _Pragma("unroll") for (int k = 0; k < 2; ++k) dst[n][k] = *(const LAS bf16x8*)(lds + PG8_SB(b, h) + boff + n * 2048 + k * 1024); } while (0)
; #define PG8_MMA(ai, bj, At, Bt) do { __builtin_amdgcn_s_setprio(1); _Pragma("unroll") for (int m = 0; m < 4; ++m) _Pragma("unroll") for (int n = 0; n < 2; ++n) _Pragma("unroll") for (int k = 0; k < 2; ++k) \
;         acc[ai][bj][m][n] = __builtin_amdgcn_mfma_f32_16x16x32_bf16(Bt[n][k], At[m][k], acc[ai][bj][m][n], 0, 0, 0); __builtin_amdgcn_s_setprio(0); } while (0)
; #define PG8_WAIT_V(n) asm volatile("s_waitcnt vmcnt(" #n ")" ::: "memory")
; #define PG8_WAIT_L(n) asm volatile("s_waitcnt lgkmcnt(" #n ")" ::: "memory")
; #define PG8_BAR __builtin_amdgcn_s_barrier()
; #define PG8_SCHED __builtin_amdgcn_sched_barrier(0)
; __device__ __forceinline__ void gemm_phase(LAS unsigned char* lds, const int K, const int G, const int c) {
;     ...
;         for (int t = 0; t < nt; t += 2) {
;             const bool last = (t == nt - 2);
;             const char* a1 = cA + (size_t)(t + 1) * kstep;
;             const char* a2 = last ? nA : cA + (size_t)(t + 2) * kstep; const char* b2 = last ? nB : cB + (size_t)(t + 2) * kstep;
;             const char* a3 = a2 + kstep; const char* b3 = b2 + kstep;
;             PG8_LDB(B0, 0, 0); PG8_LDB(B1, 0, 1); PG8_SCHED; PG8_LDA(At, 0, 0); PG8_STAGE(PG8_SA(1, 1), a1 + hstep);
;             PG8_WAIT_V(8); PG8_WAIT_L(0); PG8_BAR; PG8_MMA(0, 0, At, B0); PG8_MMA(0, 1, At, B1); PG8_BAR; PG8_SCHED;
;     ...
; #pragma unroll
;         for (int a = 0; a < 2; ++a)
; #pragma unroll
;             for (int b = 0; b < 2; ++b)
; #pragma unroll
;                 for (int m = 0; m < 4; ++m)
; #pragma unroll
;                     for (int n = 0; n < 2; ++n) acc[a][b][m][n] = (f32x4){0.f, 0.f, 0.f, 0.f};
.LBB0_1299:
	s_cmp_lt_i32 s72, 1
	s_cbranch_scc1 .LBB0_2507
	s_add_i32 s3, s72, -2
	s_add_u32 s17, s26, 0x100
	s_addc_u32 s23, s27, 0
	s_add_u32 s8, s8, 0x80
	v_mov_b32_e32 v4, 0
	s_addc_u32 s9, s9, 0
	s_mov_b32 s25, 0
	v_mov_b32_e32 v5, v4
	v_mov_b32_e32 v6, v4
	v_mov_b32_e32 v7, v4
	v_mov_b32_e32 v8, v4
	v_mov_b32_e32 v9, v4
	v_mov_b32_e32 v10, v4
	v_mov_b32_e32 v11, v4
	v_mov_b32_e32 v20, v4
	v_mov_b32_e32 v21, v4
	v_mov_b32_e32 v22, v4
	v_mov_b32_e32 v23, v4
	v_mov_b32_e32 v24, v4
	v_mov_b32_e32 v25, v4
	v_mov_b32_e32 v26, v4
	v_mov_b32_e32 v27, v4
	v_mov_b32_e32 v36, v4
	v_mov_b32_e32 v37, v4
	v_mov_b32_e32 v38, v4
	v_mov_b32_e32 v39, v4
	v_mov_b32_e32 v40, v4
	v_mov_b32_e32 v41, v4
	v_mov_b32_e32 v42, v4
	v_mov_b32_e32 v43, v4
	v_mov_b32_e32 v52, v4
	v_mov_b32_e32 v53, v4
	v_mov_b32_e32 v54, v4
	v_mov_b32_e32 v55, v4
	v_mov_b32_e32 v56, v4
	v_mov_b32_e32 v57, v4
	v_mov_b32_e32 v58, v4
	v_mov_b32_e32 v59, v4
	v_mov_b32_e32 v12, v4
	v_mov_b32_e32 v13, v4
	v_mov_b32_e32 v14, v4
	v_mov_b32_e32 v15, v4
	v_mov_b32_e32 v16, v4
	v_mov_b32_e32 v17, v4
	v_mov_b32_e32 v18, v4
	v_mov_b32_e32 v19, v4
	v_mov_b32_e32 v28, v4
	v_mov_b32_e32 v29, v4
	v_mov_b32_e32 v30, v4
	v_mov_b32_e32 v31, v4
	v_mov_b32_e32 v32, v4
	v_mov_b32_e32 v33, v4
	v_mov_b32_e32 v34, v4
	v_mov_b32_e32 v35, v4
	v_mov_b32_e32 v44, v4
	v_mov_b32_e32 v45, v4
	v_mov_b32_e32 v46, v4
	v_mov_b32_e32 v47, v4
	v_mov_b32_e32 v48, v4
	v_mov_b32_e32 v49, v4
	v_mov_b32_e32 v50, v4
	v_mov_b32_e32 v51, v4
	v_mov_b32_e32 v60, v4
	v_mov_b32_e32 v61, v4
	v_mov_b32_e32 v62, v4
	v_mov_b32_e32 v63, v4
	v_mov_b32_e32 v64, v4
	v_mov_b32_e32 v65, v4
	v_mov_b32_e32 v66, v4
	v_mov_b32_e32 v67, v4
	v_mov_b32_e32 v68, v4
	v_mov_b32_e32 v69, v4
	v_mov_b32_e32 v70, v4
	v_mov_b32_e32 v71, v4
	v_mov_b32_e32 v72, v4
	v_mov_b32_e32 v73, v4
	v_mov_b32_e32 v74, v4
	v_mov_b32_e32 v75, v4
	v_mov_b32_e32 v84, v4
	v_mov_b32_e32 v85, v4
	v_mov_b32_e32 v86, v4
	v_mov_b32_e32 v87, v4
	v_mov_b32_e32 v88, v4
	v_mov_b32_e32 v89, v4
	v_mov_b32_e32 v90, v4
	v_mov_b32_e32 v91, v4
	v_mov_b32_e32 v100, v4
	v_mov_b32_e32 v101, v4
	v_mov_b32_e32 v102, v4
	v_mov_b32_e32 v103, v4
	v_mov_b32_e32 v104, v4
	v_mov_b32_e32 v105, v4
	v_mov_b32_e32 v106, v4
	v_mov_b32_e32 v107, v4
	v_mov_b32_e32 v116, v4
	v_mov_b32_e32 v117, v4
	v_mov_b32_e32 v118, v4
	v_mov_b32_e32 v119, v4
	v_mov_b32_e32 v120, v4
	v_mov_b32_e32 v121, v4
	v_mov_b32_e32 v122, v4
	v_mov_b32_e32 v123, v4
	v_mov_b32_e32 v76, v4
	v_mov_b32_e32 v77, v4
	v_mov_b32_e32 v78, v4
	v_mov_b32_e32 v79, v4
	v_mov_b32_e32 v80, v4
	v_mov_b32_e32 v81, v4
	v_mov_b32_e32 v82, v4
	v_mov_b32_e32 v83, v4
	v_mov_b32_e32 v92, v4
	v_mov_b32_e32 v93, v4
	v_mov_b32_e32 v94, v4
	v_mov_b32_e32 v95, v4
	v_mov_b32_e32 v96, v4
	v_mov_b32_e32 v97, v4
	v_mov_b32_e32 v98, v4
	v_mov_b32_e32 v99, v4
	v_mov_b32_e32 v108, v4
	v_mov_b32_e32 v109, v4
	v_mov_b32_e32 v110, v4
	v_mov_b32_e32 v111, v4
	v_mov_b32_e32 v112, v4
	v_mov_b32_e32 v113, v4
	v_mov_b32_e32 v114, v4
	v_mov_b32_e32 v115, v4
	v_mov_b32_e32 v124, v4
	v_mov_b32_e32 v125, v4
	v_mov_b32_e32 v126, v4
	v_mov_b32_e32 v127, v4
	v_mov_b32_e32 v128, v4
	v_mov_b32_e32 v129, v4
	v_mov_b32_e32 v130, v4
	v_mov_b32_e32 v131, v4
	s_cmp_lg_u64 s[12:13], 0
	s_cbranch_scc0 .Lgp_noprio
	s_setprio 1
.Lgp_noprio:
.LBB0_1301:
	s_add_i32 s30, s25, 2
	s_add_u32 s26, s8, 0x80
	s_addc_u32 s27, s9, 0
	s_add_i32 s31, 0, 0x10000
	s_cmp_eq_u32 s3, s25
	s_cselect_b32 s27, s19, s27
	s_cselect_b32 s26, s18, s26
	v_add_u32_e32 v144, s31, v158
	s_cselect_b32 s75, s21, s23
	s_cselect_b32 s74, s20, s17
	s_add_i32 s25, 0, 0x14000
	ds_read_b128 v[140:143], v144
	ds_read_b128 v[162:165], v144 offset:1024
	ds_read_b128 v[166:169], v144 offset:2048
	ds_read_b128 v[170:173], v144 offset:3072
	v_add_u32_e32 v144, s25, v158
	ds_read_b128 v[174:177], v144
	ds_read_b128 v[178:181], v144 offset:1024
	ds_read_b128 v[182:185], v144 offset:2048
	ds_read_b128 v[186:189], v144 offset:3072
	v_lshl_add_u64 v[144:145], s[8:9], 0, v[138:139]
	s_add_i32 m0, s54, 0xc000
	ds_read_b128 v[190:193], v160
	ds_read_b128 v[194:197], v160 offset:1024
	ds_read_b128 v[198:201], v160 offset:2048
	ds_read_b128 v[202:205], v160 offset:3072
	ds_read_b128 v[206:209], v160 offset:4096
	ds_read_b128 v[210:213], v160 offset:5120
	ds_read_b128 v[214:217], v160 offset:6144
	ds_read_b128 v[218:221], v160 offset:7168
	global_load_lds_dwordx4 v[144:145], off
	v_lshl_add_u64 v[144:145], s[8:9], 0, v[136:137]
	s_add_i32 m0, s54, 0xe000
	s_nop 0
	global_load_lds_dwordx4 v[144:145], off
	s_waitcnt vmcnt(8)
	s_waitcnt lgkmcnt(0)
	s_barrier
; #define PG8_STAGE(bufoff, gbase) do { _Pragma("unroll") for (int _i = 0; _i < 2; ++_i) \
;         __builtin_amdgcn_global_load_lds((const unsigned*)((const char*)(gbase) + voff[_i]), (LAS unsigned*)(lds + (bufoff) + ldsw + _i * 8192), 16, 0, 0); } while (0)
; #define PG8_LDA(dst, b, h) do { _Pragma("unroll") for (int m = 0; m < 4; ++m) _Pragma("unroll") for (int k = 0; k < 2; ++k) dst[m][k] = *(const LAS bf16x8*)(lds + PG8_SA(b, h) + aoff + m * 2048 + k * 1024); } while (0)
; #define PG8_MMA(ai, bj, At, Bt) do { __builtin_amdgcn_s_setprio(1); _Pragma("unroll") for (int m = 0; m < 4; ++m) _Pragma("unroll") for (int n = 0; n < 2; ++n) _Pragma("unroll") for (int k = 0; k < 2; ++k) \
;         acc[ai][bj][m][n] = __builtin_amdgcn_mfma_f32_16x16x32_bf16(Bt[n][k], At[m][k], acc[ai][bj][m][n], 0, 0, 0); __builtin_amdgcn_s_setprio(0); } while (0)
; #define PG8_WAIT_V(n) asm volatile("s_waitcnt vmcnt(" #n ")" ::: "memory")
; #define PG8_WAIT_L(n) asm volatile("s_waitcnt lgkmcnt(" #n ")" ::: "memory")
; #define PG8_BAR __builtin_amdgcn_s_barrier()
; #define PG8_SCHED __builtin_amdgcn_sched_barrier(0)
; __device__ __forceinline__ void gemm_phase(LAS unsigned char* lds, const int K, const int G, const int c) {
;     ...
;             PG8_WAIT_V(8); PG8_WAIT_L(0); PG8_BAR; PG8_MMA(0, 0, At, B0); PG8_MMA(0, 1, At, B1); PG8_BAR; PG8_SCHED;
;             PG8_LDA(At, 0, 1); PG8_STAGE(PG8_SB(0, 0), b2); PG8_STAGE(PG8_SB(0, 1), b2 + hstep); PG8_STAGE(PG8_SA(0, 0), a2);
;             PG8_WAIT_V(8); PG8_WAIT_L(0); PG8_BAR; PG8_MMA(1, 0, At, B0); PG8_MMA(1, 1, At, B1); PG8_BAR; PG8_SCHED;
	s_waitcnt lgkmcnt(0)
	v_mfma_f32_16x16x32_bf16 v[128:131], v[140:143], v[190:193], v[128:131]
	v_mfma_f32_16x16x32_bf16 v[124:127], v[166:169], v[190:193], v[124:127]
	v_mfma_f32_16x16x32_bf16 v[112:115], v[140:143], v[198:201], v[112:115]
	v_mfma_f32_16x16x32_bf16 v[108:111], v[166:169], v[198:201], v[108:111]
	v_mfma_f32_16x16x32_bf16 v[96:99], v[140:143], v[206:209], v[96:99]
	v_mfma_f32_16x16x32_bf16 v[92:95], v[166:169], v[206:209], v[92:95]
	v_mfma_f32_16x16x32_bf16 v[80:83], v[140:143], v[214:217], v[80:83]
	v_mfma_f32_16x16x32_bf16 v[76:79], v[166:169], v[214:217], v[76:79]
	v_mfma_f32_16x16x32_bf16 v[128:131], v[162:165], v[194:197], v[128:131]
	v_mfma_f32_16x16x32_bf16 v[124:127], v[170:173], v[194:197], v[124:127]
	v_mfma_f32_16x16x32_bf16 v[112:115], v[162:165], v[202:205], v[112:115]
	v_mfma_f32_16x16x32_bf16 v[108:111], v[170:173], v[202:205], v[108:111]
	v_mfma_f32_16x16x32_bf16 v[96:99], v[162:165], v[210:213], v[96:99]
	v_mfma_f32_16x16x32_bf16 v[92:95], v[170:173], v[210:213], v[92:95]
	v_mfma_f32_16x16x32_bf16 v[80:83], v[162:165], v[218:221], v[80:83]
	v_mfma_f32_16x16x32_bf16 v[76:79], v[170:173], v[218:221], v[76:79]
	v_mfma_f32_16x16x32_bf16 v[120:123], v[174:177], v[190:193], v[120:123]
	v_mfma_f32_16x16x32_bf16 v[116:119], v[182:185], v[190:193], v[116:119]
	v_mfma_f32_16x16x32_bf16 v[104:107], v[174:177], v[198:201], v[104:107]
	v_mfma_f32_16x16x32_bf16 v[100:103], v[182:185], v[198:201], v[100:103]
	v_mfma_f32_16x16x32_bf16 v[88:91], v[174:177], v[206:209], v[88:91]
	v_mfma_f32_16x16x32_bf16 v[84:87], v[182:185], v[206:209], v[84:87]
	v_mfma_f32_16x16x32_bf16 v[72:75], v[174:177], v[214:217], v[72:75]
	v_mfma_f32_16x16x32_bf16 v[68:71], v[182:185], v[214:217], v[68:71]
	v_mfma_f32_16x16x32_bf16 v[120:123], v[178:181], v[194:197], v[120:123]
	v_mfma_f32_16x16x32_bf16 v[116:119], v[186:189], v[194:197], v[116:119]
	v_mfma_f32_16x16x32_bf16 v[104:107], v[178:181], v[202:205], v[104:107]
	v_mfma_f32_16x16x32_bf16 v[100:103], v[186:189], v[202:205], v[100:103]
	v_mfma_f32_16x16x32_bf16 v[88:91], v[178:181], v[210:213], v[88:91]
	v_mfma_f32_16x16x32_bf16 v[84:87], v[186:189], v[210:213], v[84:87]
	v_mfma_f32_16x16x32_bf16 v[72:75], v[178:181], v[218:221], v[72:75]
	v_mfma_f32_16x16x32_bf16 v[68:71], v[186:189], v[218:221], v[68:71]
	s_barrier
	s_add_i32 s31, s31, s47
	v_lshl_add_u64 v[144:145], s[74:75], 0, v[2:3]
	s_mov_b32 m0, s31
	ds_read_b128 v[190:193], v160 offset:16384
	ds_read_b128 v[194:197], v160 offset:17408
	ds_read_b128 v[198:201], v160 offset:18432
	ds_read_b128 v[202:205], v160 offset:19456
	ds_read_b128 v[206:209], v160 offset:20480
	ds_read_b128 v[210:213], v160 offset:21504
	ds_read_b128 v[214:217], v160 offset:22528
	ds_read_b128 v[218:221], v160 offset:23552
	global_load_lds_dwordx4 v[144:145], off
	s_add_i32 m0, s31, 0x2000
	v_lshl_add_u64 v[222:223], s[74:75], 0, v[0:1]
	s_add_u32 s74, s74, s10
	s_addc_u32 s75, s75, 0
	s_add_i32 s25, s25, s47
	global_load_lds_dwordx4 v[222:223], off
	v_lshl_add_u64 v[224:225], s[74:75], 0, v[2:3]
	s_mov_b32 m0, s25
	v_lshl_add_u64 v[226:227], s[74:75], 0, v[0:1]
	global_load_lds_dwordx4 v[224:225], off
	s_add_i32 m0, s25, 0x2000
	v_lshl_add_u64 v[228:229], s[26:27], 0, v[2:3]
	global_load_lds_dwordx4 v[226:227], off
	s_mov_b32 m0, s54
	v_lshl_add_u64 v[230:231], s[26:27], 0, v[0:1]
	global_load_lds_dwordx4 v[228:229], off
	s_mov_b32 m0, s55
	s_nop 0
	global_load_lds_dwordx4 v[230:231], off
	s_waitcnt vmcnt(8)
	s_waitcnt lgkmcnt(0)
	s_barrier
	s_waitcnt lgkmcnt(0)
	v_mfma_f32_16x16x32_bf16 v[64:67], v[140:143], v[190:193], v[64:67]
	v_mfma_f32_16x16x32_bf16 v[60:63], v[166:169], v[190:193], v[60:63]
	v_mfma_f32_16x16x32_bf16 v[48:51], v[140:143], v[198:201], v[48:51]
	v_mfma_f32_16x16x32_bf16 v[44:47], v[166:169], v[198:201], v[44:47]
	v_mfma_f32_16x16x32_bf16 v[32:35], v[140:143], v[206:209], v[32:35]
	v_mfma_f32_16x16x32_bf16 v[28:31], v[166:169], v[206:209], v[28:31]
	v_mfma_f32_16x16x32_bf16 v[16:19], v[140:143], v[214:217], v[16:19]
	v_mfma_f32_16x16x32_bf16 v[12:15], v[166:169], v[214:217], v[12:15]
	v_mfma_f32_16x16x32_bf16 v[64:67], v[162:165], v[194:197], v[64:67]
	v_mfma_f32_16x16x32_bf16 v[60:63], v[170:173], v[194:197], v[60:63]
	v_mfma_f32_16x16x32_bf16 v[48:51], v[162:165], v[202:205], v[48:51]
	v_mfma_f32_16x16x32_bf16 v[44:47], v[170:173], v[202:205], v[44:47]
	v_mfma_f32_16x16x32_bf16 v[32:35], v[162:165], v[210:213], v[32:35]
	v_mfma_f32_16x16x32_bf16 v[28:31], v[170:173], v[210:213], v[28:31]
	v_mfma_f32_16x16x32_bf16 v[16:19], v[162:165], v[218:221], v[16:19]
	v_mfma_f32_16x16x32_bf16 v[12:15], v[170:173], v[218:221], v[12:15]
	v_mfma_f32_16x16x32_bf16 v[56:59], v[174:177], v[190:193], v[56:59]
	v_mfma_f32_16x16x32_bf16 v[52:55], v[182:185], v[190:193], v[52:55]
	v_mfma_f32_16x16x32_bf16 v[40:43], v[174:177], v[198:201], v[40:43]
	v_mfma_f32_16x16x32_bf16 v[36:39], v[182:185], v[198:201], v[36:39]
	v_mfma_f32_16x16x32_bf16 v[24:27], v[174:177], v[206:209], v[24:27]
	v_mfma_f32_16x16x32_bf16 v[20:23], v[182:185], v[206:209], v[20:23]
	v_mfma_f32_16x16x32_bf16 v[8:11], v[174:177], v[214:217], v[8:11]
	v_mfma_f32_16x16x32_bf16 v[4:7], v[182:185], v[214:217], v[4:7]
	v_mfma_f32_16x16x32_bf16 v[56:59], v[178:181], v[194:197], v[56:59]
	v_mfma_f32_16x16x32_bf16 v[52:55], v[186:189], v[194:197], v[52:55]
	v_mfma_f32_16x16x32_bf16 v[40:43], v[178:181], v[202:205], v[40:43]
	v_mfma_f32_16x16x32_bf16 v[36:39], v[186:189], v[202:205], v[36:39]
	v_mfma_f32_16x16x32_bf16 v[24:27], v[178:181], v[210:213], v[24:27]
	v_mfma_f32_16x16x32_bf16 v[20:23], v[186:189], v[210:213], v[20:23]
	v_mfma_f32_16x16x32_bf16 v[8:11], v[178:181], v[218:221], v[8:11]
	v_mfma_f32_16x16x32_bf16 v[4:7], v[186:189], v[218:221], v[4:7]
	s_barrier
; #define PG8_STAGE(bufoff, gbase) do { _Pragma("unroll") for (int _i = 0; _i < 2; ++_i) \
;         __builtin_amdgcn_global_load_lds((const unsigned*)((const char*)(gbase) + voff[_i]), (LAS unsigned*)(lds + (bufoff) + ldsw + _i * 8192), 16, 0, 0); } while (0)
; #define PG8_LDA(dst, b, h) do { _Pragma("unroll") for (int m = 0; m < 4; ++m) _Pragma("unroll") for (int k = 0; k < 2; ++k) dst[m][k] = *(const LAS bf16x8*)(lds + PG8_SA(b, h) + aoff + m * 2048 + k * 1024); } while (0)
; #define PG8_LDB(dst, b, h) do { _Pragma("unroll") for (int n = 0; n < 2; ++n) _Pragma("unroll") for (int k = 0; k < 2; ++k) dst[n][k] = *(const LAS bf16x8*)(lds + PG8_SB(b, h) + boff + n * 2048 + k * 1024); } while (0)
; #define PG8_MMA(ai, bj, At, Bt) do { __builtin_amdgcn_s_setprio(1); _Pragma("unroll") for (int m = 0; m < 4; ++m) _Pragma("unroll") for (int n = 0; n < 2; ++n) _Pragma("unroll") for (int k = 0; k < 2; ++k) \
;         acc[ai][bj][m][n] = __builtin_amdgcn_mfma_f32_16x16x32_bf16(Bt[n][k], At[m][k], acc[ai][bj][m][n], 0, 0, 0); __builtin_amdgcn_s_setprio(0); } while (0)
; #define PG8_WAIT_V(n) asm volatile("s_waitcnt vmcnt(" #n ")" ::: "memory")
; #define PG8_WAIT_L(n) asm volatile("s_waitcnt lgkmcnt(" #n ")" ::: "memory")
; #define PG8_BAR __builtin_amdgcn_s_barrier()
; #define PG8_SCHED __builtin_amdgcn_sched_barrier(0)
; __device__ __forceinline__ void gemm_phase(LAS unsigned char* lds, const int K, const int G, const int c) {
;     ...
;             PG8_LDB(B0, 1, 0); PG8_LDB(B1, 1, 1); PG8_SCHED; PG8_LDA(At, 1, 0); PG8_STAGE(PG8_SA(0, 1), a2 + hstep);
;             PG8_WAIT_V(8); PG8_WAIT_L(0); PG8_BAR; PG8_MMA(0, 0, At, B0); PG8_MMA(0, 1, At, B1); PG8_BAR; PG8_SCHED;
	s_add_i32 s25, 0, 0x18000
	v_add_u32_e32 v161, s25, v158
	s_add_i32 s31, 0, 0x1c000
	ds_read_b128 v[140:143], v161
	ds_read_b128 v[162:165], v161 offset:1024
	ds_read_b128 v[166:169], v161 offset:2048
	ds_read_b128 v[170:173], v161 offset:3072
	v_add_u32_e32 v161, s31, v158
	ds_read_b128 v[174:177], v161
	ds_read_b128 v[178:181], v161 offset:1024
	ds_read_b128 v[182:185], v161 offset:2048
	ds_read_b128 v[186:189], v161 offset:3072
	s_add_u32 s26, s26, s10
	s_addc_u32 s27, s27, 0
	s_mov_b32 m0, s66
	v_lshl_add_u64 v[232:233], s[26:27], 0, v[2:3]
	ds_read_b128 v[190:193], v160 offset:32768
	ds_read_b128 v[194:197], v160 offset:33792
	ds_read_b128 v[198:201], v160 offset:34816
	ds_read_b128 v[202:205], v160 offset:35840
	ds_read_b128 v[206:209], v160 offset:36864
	ds_read_b128 v[210:213], v160 offset:37888
	ds_read_b128 v[214:217], v160 offset:38912
	ds_read_b128 v[218:221], v160 offset:39936
	global_load_lds_dwordx4 v[232:233], off
	v_lshl_add_u64 v[232:233], s[26:27], 0, v[0:1]
	s_mov_b32 m0, s67
	s_nop 0
	global_load_lds_dwordx4 v[232:233], off
	s_waitcnt vmcnt(8)
	s_waitcnt lgkmcnt(0)
	s_barrier
	s_waitcnt lgkmcnt(0)
	v_mfma_f32_16x16x32_bf16 v[128:131], v[140:143], v[190:193], v[128:131]
	v_mfma_f32_16x16x32_bf16 v[124:127], v[166:169], v[190:193], v[124:127]
	v_mfma_f32_16x16x32_bf16 v[112:115], v[140:143], v[198:201], v[112:115]
	v_mfma_f32_16x16x32_bf16 v[108:111], v[166:169], v[198:201], v[108:111]
	v_mfma_f32_16x16x32_bf16 v[96:99], v[140:143], v[206:209], v[96:99]
	v_mfma_f32_16x16x32_bf16 v[92:95], v[166:169], v[206:209], v[92:95]
	v_mfma_f32_16x16x32_bf16 v[80:83], v[140:143], v[214:217], v[80:83]
	v_mfma_f32_16x16x32_bf16 v[76:79], v[166:169], v[214:217], v[76:79]
	v_mfma_f32_16x16x32_bf16 v[128:131], v[162:165], v[194:197], v[128:131]
	v_mfma_f32_16x16x32_bf16 v[124:127], v[170:173], v[194:197], v[124:127]
	v_mfma_f32_16x16x32_bf16 v[112:115], v[162:165], v[202:205], v[112:115]
	v_mfma_f32_16x16x32_bf16 v[108:111], v[170:173], v[202:205], v[108:111]
	v_mfma_f32_16x16x32_bf16 v[96:99], v[162:165], v[210:213], v[96:99]
	v_mfma_f32_16x16x32_bf16 v[92:95], v[170:173], v[210:213], v[92:95]
	v_mfma_f32_16x16x32_bf16 v[80:83], v[162:165], v[218:221], v[80:83]
	v_mfma_f32_16x16x32_bf16 v[76:79], v[170:173], v[218:221], v[76:79]
	v_mfma_f32_16x16x32_bf16 v[120:123], v[174:177], v[190:193], v[120:123]
	v_mfma_f32_16x16x32_bf16 v[116:119], v[182:185], v[190:193], v[116:119]
	v_mfma_f32_16x16x32_bf16 v[104:107], v[174:177], v[198:201], v[104:107]
	v_mfma_f32_16x16x32_bf16 v[100:103], v[182:185], v[198:201], v[100:103]
	v_mfma_f32_16x16x32_bf16 v[88:91], v[174:177], v[206:209], v[88:91]
	v_mfma_f32_16x16x32_bf16 v[84:87], v[182:185], v[206:209], v[84:87]
	v_mfma_f32_16x16x32_bf16 v[72:75], v[174:177], v[214:217], v[72:75]
	v_mfma_f32_16x16x32_bf16 v[68:71], v[182:185], v[214:217], v[68:71]
	v_mfma_f32_16x16x32_bf16 v[120:123], v[178:181], v[194:197], v[120:123]
	v_mfma_f32_16x16x32_bf16 v[116:119], v[186:189], v[194:197], v[116:119]
	v_mfma_f32_16x16x32_bf16 v[104:107], v[178:181], v[202:205], v[104:107]
	v_mfma_f32_16x16x32_bf16 v[100:103], v[186:189], v[202:205], v[100:103]
	v_mfma_f32_16x16x32_bf16 v[88:91], v[178:181], v[210:213], v[88:91]
	v_mfma_f32_16x16x32_bf16 v[84:87], v[186:189], v[210:213], v[84:87]
	v_mfma_f32_16x16x32_bf16 v[72:75], v[178:181], v[218:221], v[72:75]
	v_mfma_f32_16x16x32_bf16 v[68:71], v[186:189], v[218:221], v[68:71]
	s_barrier
; #define PG8_STAGE(bufoff, gbase) do { _Pragma("unroll") for (int _i = 0; _i < 2; ++_i) \
;         __builtin_amdgcn_global_load_lds((const unsigned*)((const char*)(gbase) + voff[_i]), (LAS unsigned*)(lds + (bufoff) + ldsw + _i * 8192), 16, 0, 0); } while (0)
; #define PG8_LDA(dst, b, h) do { _Pragma("unroll") for (int m = 0; m < 4; ++m) _Pragma("unroll") for (int k = 0; k < 2; ++k) dst[m][k] = *(const LAS bf16x8*)(lds + PG8_SA(b, h) + aoff + m * 2048 + k * 1024); } while (0)
; #define PG8_MMA(ai, bj, At, Bt) do { __builtin_amdgcn_s_setprio(1); _Pragma("unroll") for (int m = 0; m < 4; ++m) _Pragma("unroll") for (int n = 0; n < 2; ++n) _Pragma("unroll") for (int k = 0; k < 2; ++k) \
;         acc[ai][bj][m][n] = __builtin_amdgcn_mfma_f32_16x16x32_bf16(Bt[n][k], At[m][k], acc[ai][bj][m][n], 0, 0, 0); __builtin_amdgcn_s_setprio(0); } while (0)
; #define PG8_WAIT_V(n) asm volatile("s_waitcnt vmcnt(" #n ")" ::: "memory")
; #define PG8_WAIT_L(n) asm volatile("s_waitcnt lgkmcnt(" #n ")" ::: "memory")
; #define PG8_BAR __builtin_amdgcn_s_barrier()
; #define PG8_SCHED __builtin_amdgcn_sched_barrier(0)
; __device__ __forceinline__ void gemm_phase(LAS unsigned char* lds, const int K, const int G, const int c) {
;     ...
;             PG8_LDA(At, 1, 1); PG8_STAGE(PG8_SB(1, 0), b3); PG8_STAGE(PG8_SB(1, 1), b3 + hstep); PG8_STAGE(PG8_SA(1, 0), a3);
;             PG8_WAIT_V(8); PG8_WAIT_L(0); PG8_BAR; PG8_MMA(1, 0, At, B0); PG8_MMA(1, 1, At, B1); PG8_BAR; PG8_SCHED;
;         }
;         if (wr == 0) PG8_BAR;
	s_add_i32 s25, s25, s47
	v_lshl_add_u64 v[144:145], v[144:145], 0, s[48:49]
	s_mov_b32 m0, s25
	ds_read_b128 v[190:193], v160 offset:49152
	ds_read_b128 v[194:197], v160 offset:50176
	ds_read_b128 v[198:201], v160 offset:51200
	ds_read_b128 v[202:205], v160 offset:52224
	ds_read_b128 v[206:209], v160 offset:53248
	ds_read_b128 v[210:213], v160 offset:54272
	ds_read_b128 v[214:217], v160 offset:55296
	ds_read_b128 v[218:221], v160 offset:56320
	global_load_lds_dwordx4 v[144:145], off
	v_lshl_add_u64 v[144:145], v[222:223], 0, s[48:49]
	s_add_i32 m0, s25, 0x2000
	s_add_i32 s25, s31, s47
	global_load_lds_dwordx4 v[144:145], off
	v_lshl_add_u64 v[144:145], v[224:225], 0, s[48:49]
	s_mov_b32 m0, s25
	s_nop 0
	global_load_lds_dwordx4 v[144:145], off
	v_lshl_add_u64 v[144:145], v[226:227], 0, s[48:49]
	s_add_i32 m0, s25, 0x2000
	s_nop 0
	global_load_lds_dwordx4 v[144:145], off
	v_lshl_add_u64 v[144:145], v[228:229], 0, s[48:49]
	s_mov_b32 m0, s28
	s_nop 0
	global_load_lds_dwordx4 v[144:145], off
	v_lshl_add_u64 v[144:145], v[230:231], 0, s[48:49]
	s_mov_b32 m0, s38
	s_nop 0
	global_load_lds_dwordx4 v[144:145], off
	s_waitcnt vmcnt(8)
	s_waitcnt lgkmcnt(0)
	s_barrier
	s_waitcnt lgkmcnt(0)
	v_mfma_f32_16x16x32_bf16 v[64:67], v[140:143], v[190:193], v[64:67]
	v_mfma_f32_16x16x32_bf16 v[60:63], v[166:169], v[190:193], v[60:63]
	v_mfma_f32_16x16x32_bf16 v[48:51], v[140:143], v[198:201], v[48:51]
	v_mfma_f32_16x16x32_bf16 v[44:47], v[166:169], v[198:201], v[44:47]
	v_mfma_f32_16x16x32_bf16 v[32:35], v[140:143], v[206:209], v[32:35]
	v_mfma_f32_16x16x32_bf16 v[28:31], v[166:169], v[206:209], v[28:31]
	v_mfma_f32_16x16x32_bf16 v[16:19], v[140:143], v[214:217], v[16:19]
	v_mfma_f32_16x16x32_bf16 v[12:15], v[166:169], v[214:217], v[12:15]
	v_mfma_f32_16x16x32_bf16 v[64:67], v[162:165], v[194:197], v[64:67]
	v_mfma_f32_16x16x32_bf16 v[60:63], v[170:173], v[194:197], v[60:63]
	v_mfma_f32_16x16x32_bf16 v[48:51], v[162:165], v[202:205], v[48:51]
	v_mfma_f32_16x16x32_bf16 v[44:47], v[170:173], v[202:205], v[44:47]
	v_mfma_f32_16x16x32_bf16 v[32:35], v[162:165], v[210:213], v[32:35]
	v_mfma_f32_16x16x32_bf16 v[28:31], v[170:173], v[210:213], v[28:31]
	v_mfma_f32_16x16x32_bf16 v[16:19], v[162:165], v[218:221], v[16:19]
	v_mfma_f32_16x16x32_bf16 v[12:15], v[170:173], v[218:221], v[12:15]
	v_mfma_f32_16x16x32_bf16 v[56:59], v[174:177], v[190:193], v[56:59]
	v_mfma_f32_16x16x32_bf16 v[52:55], v[182:185], v[190:193], v[52:55]
	v_mfma_f32_16x16x32_bf16 v[40:43], v[174:177], v[198:201], v[40:43]
	v_mfma_f32_16x16x32_bf16 v[36:39], v[182:185], v[198:201], v[36:39]
	v_mfma_f32_16x16x32_bf16 v[24:27], v[174:177], v[206:209], v[24:27]
	v_mfma_f32_16x16x32_bf16 v[20:23], v[182:185], v[206:209], v[20:23]
	v_mfma_f32_16x16x32_bf16 v[8:11], v[174:177], v[214:217], v[8:11]
	v_mfma_f32_16x16x32_bf16 v[4:7], v[182:185], v[214:217], v[4:7]
	v_mfma_f32_16x16x32_bf16 v[56:59], v[178:181], v[194:197], v[56:59]
	v_mfma_f32_16x16x32_bf16 v[52:55], v[186:189], v[194:197], v[52:55]
	v_mfma_f32_16x16x32_bf16 v[40:43], v[178:181], v[202:205], v[40:43]
	v_mfma_f32_16x16x32_bf16 v[36:39], v[186:189], v[202:205], v[36:39]
	v_mfma_f32_16x16x32_bf16 v[24:27], v[178:181], v[210:213], v[24:27]
	v_mfma_f32_16x16x32_bf16 v[20:23], v[186:189], v[210:213], v[20:23]
	v_mfma_f32_16x16x32_bf16 v[8:11], v[178:181], v[218:221], v[8:11]
	v_mfma_f32_16x16x32_bf16 v[4:7], v[186:189], v[218:221], v[4:7]
	s_barrier
	s_add_u32 s17, s17, 0x100
	s_addc_u32 s23, s23, 0
	s_add_u32 s8, s8, 0x100
	s_addc_u32 s9, s9, 0
	s_cmp_ge_i32 s30, s72
	s_mov_b32 s25, s30
	s_cbranch_scc0 .LBB0_1301
	s_setprio 0
	s_and_b64 vcc, exec, s[14:15]
	s_cbranch_vccz .LBB0_1304
